# GEMM K-loop head padded to a 64-byte boundary (4 s_nop before the tile loop)
# speedup vs baseline: 1.0031x; 1.0031x over previous
; #define WAIT_V(n) asm volatile("s_waitcnt vmcnt(" #n ")" ::: "memory")
; #define BAR __builtin_amdgcn_s_barrier()
; #define STG(P, PTR, LD, O0) do { const bf16_t* _g = (PTR); \
;     __builtin_amdgcn_global_load_lds((const unsigned*)(_g + O0), (lds_u32*)((P) + swave * 1024), 16, 0, 0); \
;     __builtin_amdgcn_global_load_lds((const unsigned*)(_g + (size_t)64 * (LD) + O0), (lds_u32*)((P) + swave * 1024 + 8192), 16, 0, 0); } while (0)
; #define WAIT_V(n) asm volatile("s_waitcnt vmcnt(" #n ")" ::: "memory")
; #define BAR __builtin_amdgcn_s_barrier()
; __device__ __forceinline__ void gemm_stream(int swave, const GemmJob& J, char* shm, int vb, int G) {
;     ...
;   const int wid = tidx >> 6, lane = tidx & 63, wr = wid >> 2, wc = wid & 3, fr = lane & 15, fq = lane >> 4;
;   unsigned offA0, offA1, offB0;
;   { int _r, _c; stage_rc(tidx * 16, _r, _c); offA0 = _r * lda + _c; offA1 = _r * lda1 + _c; const int _rb = (_r & ~31) + perm32(_r & 31); offB0 = _rb * ldb + _c; }
;   const size_t hB = (size_t)128 * ldb;
;   int cg, cbrow, cbcol; const bf16_t* cA; const bf16_t* cA1; const bf16_t* cB;
;   auto decode = [&](int id, int& g, int& brow, int& bcol, const bf16_t*& pA, const bf16_t*& pA1, const bf16_t*& pB) {
;     int pm, pn; g = 0;
;     if (J.nb == 1) tile_map(id, J.nM, J.nN, pm, pn);
;     else { g = id / per; const int rem = id - g * per; pm = rem / J.nN; pn = rem - pm * J.nN; }
;     brow = pm * 256; bcol = pn * 256;
;     pA = J.A + (size_t)g * J.strideA + (size_t)brow * lda; pA1 = J.A1 + (size_t)g * J.strideA + (size_t)brow * lda1; pB = J.Bt + (size_t)g * J.strideB + (size_t)bcol * ldb;
;   };
;   int id = vb;
;   decode(id, cg, cbrow, cbcol, cA, cA1, cB);
;   f32x4 acc[2][2][4][2] = {};
;   bf16x8 At[4][2], B0[2][2], B1[2][2];
;   STG(SB(0, 0), cB, ldb, offB0); STGA(SA(0, 0), cA, cA1, 0, 0); STG(SB(0, 1), cB + hB, ldb, offB0); STGA(SA(0, 1), cA, cA1, 0, 1);
;   if (wr == 1) BAR;
;   WAIT_V(4); BAR;
;   STG(SB(1, 0), cB + 64, ldb, offB0); STGA(SA(1, 0), cA, cA1, 1, 0); STG(SB(1, 1), cB + hB + 64, ldb, offB0);
;   WAIT_V(6); BAR;
.LBB0_725:
	s_or_b64 exec, exec, s[6:7]
	v_mad_u64_u32 v[138:139], s[6:7], v17, s37, v[2:3]
	s_mul_i32 s6, s10, s37
	s_mul_hi_u32 s7, s5, s37
	s_add_i32 s7, s7, s6
	s_mul_i32 s6, s5, s37
	s_lshr_b32 s49, s76, 6
	s_lshl_b64 s[6:7], s[6:7], 1
	v_readlane_b32 s10, v247, 55
	v_readlane_b32 s11, v247, 56
	s_add_u32 s16, s10, s6
	s_addc_u32 s17, s11, s7
	s_add_u32 s50, s10, 0xc000000
	v_readlane_b32 s7, v247, 28
	s_addc_u32 s51, s11, 0
	s_add_i32 s6, s7, s89
	v_lshl_add_u64 v[4:5], v[4:5], 0, s[22:23]
	s_mov_b32 m0, s6
	s_waitcnt vmcnt(4)
	s_barrier
	global_load_lds_dwordx4 v[4:5], off
	v_lshl_add_u64 v[4:5], v[6:7], 0, s[22:23]
	s_add_i32 m0, s6, 0x2000
	s_add_i32 s54, s42, 0x8000
	global_load_lds_dwordx4 v[4:5], off
	v_lshl_add_u64 v[4:5], v[8:9], 0, s[22:23]
	s_mov_b32 m0, s54
	s_add_i32 s55, s42, 0xa000
	v_readlane_b32 s10, v247, 29
	global_load_lds_dwordx4 v[4:5], off
	v_lshl_add_u64 v[4:5], v[10:11], 0, s[22:23]
	s_mov_b32 m0, s55
	s_add_i32 s6, s10, s89
	global_load_lds_dwordx4 v[4:5], off
	v_lshl_add_u64 v[4:5], v[12:13], 0, s[22:23]
	s_mov_b32 m0, s6
	v_and_b32_e32 v1, 15, v135
	global_load_lds_dwordx4 v[4:5], off
	v_lshl_add_u64 v[4:5], v[14:15], 0, s[22:23]
	s_add_i32 m0, s6, 0x2000
	v_bfe_u32 v19, v135, 4, 2
	global_load_lds_dwordx4 v[4:5], off
	v_lshlrev_b32_e32 v4, 2, v135
	v_lshlrev_b32_e32 v6, 4, v19
	v_lshlrev_b32_e32 v2, 6, v1
	v_and_b32_e32 v7, 32, v4
	v_bitop3_b32 v8, v6, v7, v2 bitop3:0x36
	s_add_i32 s6, 0, 0x10000
	v_add_u32_e32 v9, s6, v8
	s_add_i32 s6, 0, 0x14000
	v_add_u32_e32 v10, s6, v8
	v_lshlrev_b32_e32 v14, 6, v135
	s_movk_i32 s6, 0x3c0
	v_bfe_u32 v18, v135, 6, 2
	s_waitcnt vmcnt(6)
	v_lshlrev_b32_e32 v13, 13, v16
	v_and_or_b32 v6, v14, s6, v6
	v_lshlrev_b32_e32 v5, 12, v18
	v_add_u32_e32 v11, s7, v8
	v_add_u32_e32 v12, s10, v8
	v_lshlrev_b32_e32 v2, 5, v18
	v_lshlrev_b32_e32 v4, 3, v19
	v_add_u32_e32 v8, 0, v8
	v_xad_u32 v6, v6, v7, 0
	v_or_b32_e32 v7, 0x800, v13
	v_or_b32_e32 v14, 0x1000, v13
	v_or_b32_e32 v15, 0x1800, v13
	v_lshl_or_b32 v1, v16, 6, v1
	v_add_u32_e32 v139, v9, v5
	v_add_u32_e32 v144, v8, v13
	v_add_u32_e32 v145, v6, v7
	v_add_u32_e32 v159, v6, v14
	v_add_u32_e32 v160, v6, v15
	v_add_u32_e32 v161, v10, v5
	v_add_u32_e32 v162, v11, v5
	v_add_u32_e32 v163, v12, v5
	v_lshlrev_b32_e32 v140, 1, v2
	v_lshlrev_b32_e32 v142, 1, v4
	s_mov_b64 s[10:11], s[8:9]
	s_mov_b64 s[12:13], s[16:17]
	s_mov_b64 s[14:15], s[2:3]
	s_barrier
	s_nop 0
	s_nop 0
	s_nop 0
	s_nop 0
